# FF2 layer 0: per-row rstd from the epilogue's own sums of squares (1 KB partial records per tile), no second pass over X
# speedup vs baseline: 1.0331x; 1.0064x over previous
.LBB0_1460:
	ds_read_b128 v[144:147], v155
	ds_read_b128 v[148:151], v155 offset:1024
	ds_read_b128 v[158:161], v155 offset:2048
	ds_read_b128 v[162:165], v155 offset:3072
	s_add_u32 s33, s52, 0x4000
	s_addc_u32 s54, s53, 0
	s_cmp_eq_u32 s86, 60
	s_cselect_b32 s58, s82, s33
	s_cselect_b32 s59, s37, s54
	s_cselect_b32 s54, s83, s84
	s_cselect_b32 s55, s35, s85
	s_add_u32 s56, s58, 0x8000
	s_addc_u32 s57, s59, 0
	v_lshl_add_u64 v[206:207], s[52:53], 0, v[138:139]
	s_add_i32 m0, s64, 0xc000
	ds_read_b128 v[166:169], v156
	ds_read_b128 v[178:181], v156 offset:1024
	ds_read_b128 v[182:185], v156 offset:2048
	ds_read_b128 v[186:189], v156 offset:3072
	ds_read_b128 v[190:193], v156 offset:4096
	ds_read_b128 v[194:197], v156 offset:5120
	ds_read_b128 v[198:201], v156 offset:6144
	ds_read_b128 v[202:205], v156 offset:7168
	global_load_lds_dwordx4 v[206:207], off
	v_lshl_add_u64 v[206:207], s[52:53], 0, v[136:137]
	s_add_i32 m0, s64, 0xe000
	s_nop 0
	global_load_lds_dwordx4 v[206:207], off
	s_waitcnt lgkmcnt(8)
	s_barrier
	s_waitcnt lgkmcnt(0)
	s_setprio 1
	s_waitcnt lgkmcnt(0)
	v_mfma_f32_16x16x32_bf16 v[124:127], v[144:147], v[166:169], v[124:127]
	v_mfma_f32_16x16x32_bf16 v[120:123], v[158:161], v[166:169], v[120:123]
	v_mfma_f32_16x16x32_bf16 v[108:111], v[144:147], v[182:185], v[108:111]
	v_mfma_f32_16x16x32_bf16 v[104:107], v[158:161], v[182:185], v[104:107]
	v_mfma_f32_16x16x32_bf16 v[92:95], v[144:147], v[190:193], v[92:95]
	v_mfma_f32_16x16x32_bf16 v[88:91], v[158:161], v[190:193], v[88:91]
	v_mfma_f32_16x16x32_bf16 v[76:79], v[144:147], v[198:201], v[76:79]
	v_mfma_f32_16x16x32_bf16 v[72:75], v[158:161], v[198:201], v[72:75]
	v_mfma_f32_16x16x32_bf16 v[124:127], v[148:151], v[178:181], v[124:127]
	v_mfma_f32_16x16x32_bf16 v[120:123], v[162:165], v[178:181], v[120:123]
	v_mfma_f32_16x16x32_bf16 v[108:111], v[148:151], v[186:189], v[108:111]
	v_mfma_f32_16x16x32_bf16 v[104:107], v[162:165], v[186:189], v[104:107]
	v_mfma_f32_16x16x32_bf16 v[92:95], v[148:151], v[194:197], v[92:95]
	v_mfma_f32_16x16x32_bf16 v[88:91], v[162:165], v[194:197], v[88:91]
	v_mfma_f32_16x16x32_bf16 v[76:79], v[148:151], v[202:205], v[76:79]
	v_mfma_f32_16x16x32_bf16 v[72:75], v[162:165], v[202:205], v[72:75]
	s_setprio 0
	s_barrier
	s_add_i32 s33, s74, s63
	v_lshl_add_u64 v[222:223], s[54:55], 0, v[132:133]
	s_mov_b32 m0, s33
	ds_read_b128 v[206:209], v157
	ds_read_b128 v[210:213], v157 offset:1024
	ds_read_b128 v[214:217], v157 offset:2048
	ds_read_b128 v[218:221], v157 offset:3072
	global_load_lds_dwordx4 v[222:223], off
	v_lshl_add_u64 v[224:225], s[54:55], 0, v[128:129]
	s_add_i32 m0, s33, 0x2000
	s_nop 0
	global_load_lds_dwordx4 v[224:225], off
	s_barrier
	s_waitcnt lgkmcnt(0)
	s_setprio 1
	s_waitcnt lgkmcnt(0)
	v_mfma_f32_16x16x32_bf16 v[116:119], v[206:209], v[166:169], v[116:119]
	v_mfma_f32_16x16x32_bf16 v[112:115], v[214:217], v[166:169], v[112:115]
	v_mfma_f32_16x16x32_bf16 v[100:103], v[206:209], v[182:185], v[100:103]
	v_mfma_f32_16x16x32_bf16 v[96:99], v[214:217], v[182:185], v[96:99]
	v_mfma_f32_16x16x32_bf16 v[84:87], v[206:209], v[190:193], v[84:87]
	v_mfma_f32_16x16x32_bf16 v[80:83], v[214:217], v[190:193], v[80:83]
	v_mfma_f32_16x16x32_bf16 v[68:71], v[206:209], v[198:201], v[68:71]
	v_mfma_f32_16x16x32_bf16 v[64:67], v[214:217], v[198:201], v[64:67]
	v_mfma_f32_16x16x32_bf16 v[116:119], v[210:213], v[178:181], v[116:119]
	v_mfma_f32_16x16x32_bf16 v[112:115], v[218:221], v[178:181], v[112:115]
	v_mfma_f32_16x16x32_bf16 v[100:103], v[210:213], v[186:189], v[100:103]
	v_mfma_f32_16x16x32_bf16 v[96:99], v[218:221], v[186:189], v[96:99]
	v_mfma_f32_16x16x32_bf16 v[84:87], v[210:213], v[194:197], v[84:87]
	v_mfma_f32_16x16x32_bf16 v[80:83], v[218:221], v[194:197], v[80:83]
	v_mfma_f32_16x16x32_bf16 v[68:71], v[210:213], v[202:205], v[68:71]
	v_mfma_f32_16x16x32_bf16 v[64:67], v[218:221], v[202:205], v[64:67]
	s_setprio 0
	s_mov_b32 m0, s64
	v_lshl_add_u64 v[226:227], s[58:59], 0, v[134:135]
	s_barrier
	ds_read_b128 v[166:169], v156 offset:16384
	ds_read_b128 v[178:181], v156 offset:17408
	ds_read_b128 v[182:185], v156 offset:18432
	ds_read_b128 v[186:189], v156 offset:19456
	ds_read_b128 v[190:193], v156 offset:20480
	ds_read_b128 v[194:197], v156 offset:21504
	ds_read_b128 v[198:201], v156 offset:22528
	ds_read_b128 v[202:205], v156 offset:23552
	global_load_lds_dwordx4 v[226:227], off
	v_lshl_add_u64 v[226:227], s[58:59], 0, v[130:131]
	s_mov_b32 m0, s65
	s_nop 0
	global_load_lds_dwordx4 v[226:227], off
	s_barrier
	s_waitcnt lgkmcnt(0)
	s_setprio 1
	s_waitcnt lgkmcnt(0)
	v_mfma_f32_16x16x32_bf16 v[60:63], v[144:147], v[166:169], v[60:63]
	v_mfma_f32_16x16x32_bf16 v[56:59], v[158:161], v[166:169], v[56:59]
	v_mfma_f32_16x16x32_bf16 v[44:47], v[144:147], v[182:185], v[44:47]
	v_mfma_f32_16x16x32_bf16 v[40:43], v[158:161], v[182:185], v[40:43]
	v_mfma_f32_16x16x32_bf16 v[28:31], v[144:147], v[190:193], v[28:31]
	v_mfma_f32_16x16x32_bf16 v[24:27], v[158:161], v[190:193], v[24:27]
	v_mfma_f32_16x16x32_bf16 v[12:15], v[144:147], v[198:201], v[12:15]
	v_mfma_f32_16x16x32_bf16 v[8:11], v[158:161], v[198:201], v[8:11]
	v_mfma_f32_16x16x32_bf16 v[60:63], v[148:151], v[178:181], v[60:63]
	v_mfma_f32_16x16x32_bf16 v[56:59], v[162:165], v[178:181], v[56:59]
	v_mfma_f32_16x16x32_bf16 v[44:47], v[148:151], v[186:189], v[44:47]
	v_mfma_f32_16x16x32_bf16 v[40:43], v[162:165], v[186:189], v[40:43]
	v_mfma_f32_16x16x32_bf16 v[28:31], v[148:151], v[194:197], v[28:31]
	v_mfma_f32_16x16x32_bf16 v[24:27], v[162:165], v[194:197], v[24:27]
	v_mfma_f32_16x16x32_bf16 v[12:15], v[148:151], v[202:205], v[12:15]
	v_mfma_f32_16x16x32_bf16 v[8:11], v[162:165], v[202:205], v[8:11]
	s_setprio 0
	s_barrier
	s_add_u32 s88, s54, 0x100000
	s_addc_u32 s89, s55, 0
	s_add_i32 s33, s75, s63
	v_lshl_add_u64 v[144:145], s[88:89], 0, v[132:133]
	s_mov_b32 m0, s33
	s_nop 0
	global_load_lds_dwordx4 v[144:145], off
	v_lshl_add_u64 v[144:145], s[88:89], 0, v[128:129]
	s_add_i32 m0, s33, 0x2000
	s_nop 0
	global_load_lds_dwordx4 v[144:145], off
	s_waitcnt vmcnt(6)
	s_barrier
	s_setprio 1
	v_mfma_f32_16x16x32_bf16 v[52:55], v[206:209], v[166:169], v[52:55]
	v_mfma_f32_16x16x32_bf16 v[48:51], v[214:217], v[166:169], v[48:51]
	v_mfma_f32_16x16x32_bf16 v[36:39], v[206:209], v[182:185], v[36:39]
	v_mfma_f32_16x16x32_bf16 v[32:35], v[214:217], v[182:185], v[32:35]
	v_mfma_f32_16x16x32_bf16 v[20:23], v[206:209], v[190:193], v[20:23]
	v_mfma_f32_16x16x32_bf16 v[16:19], v[214:217], v[190:193], v[16:19]
	v_mfma_f32_16x16x32_bf16 v[4:7], v[206:209], v[198:201], v[4:7]
	v_mfma_f32_16x16x32_bf16 v[0:3], v[214:217], v[198:201], v[0:3]
	v_mfma_f32_16x16x32_bf16 v[52:55], v[210:213], v[178:181], v[52:55]
	v_mfma_f32_16x16x32_bf16 v[48:51], v[218:221], v[178:181], v[48:51]
	v_mfma_f32_16x16x32_bf16 v[36:39], v[210:213], v[186:189], v[36:39]
	v_mfma_f32_16x16x32_bf16 v[32:35], v[218:221], v[186:189], v[32:35]
	v_mfma_f32_16x16x32_bf16 v[20:23], v[210:213], v[194:197], v[20:23]
	v_mfma_f32_16x16x32_bf16 v[16:19], v[218:221], v[194:197], v[16:19]
	v_mfma_f32_16x16x32_bf16 v[4:7], v[210:213], v[202:205], v[4:7]
	v_mfma_f32_16x16x32_bf16 v[0:3], v[218:221], v[202:205], v[0:3]
	s_setprio 0
	s_add_i32 s33, 0, 0x18000
	v_add_u32_e32 v162, s33, v153
	s_barrier
	ds_read_b128 v[144:147], v162
	ds_read_b128 v[148:151], v162 offset:1024
	ds_read_b128 v[158:161], v162 offset:2048
	ds_read_b128 v[162:165], v162 offset:3072
	s_add_u32 s58, s58, 0x4000
	s_addc_u32 s59, s59, 0
	s_mov_b32 m0, s66
	v_lshl_add_u64 v[206:207], s[58:59], 0, v[134:135]
	ds_read_b128 v[166:169], v156 offset:32768
	ds_read_b128 v[178:181], v156 offset:33792
	ds_read_b128 v[182:185], v156 offset:34816
	ds_read_b128 v[186:189], v156 offset:35840
	ds_read_b128 v[190:193], v156 offset:36864
	ds_read_b128 v[194:197], v156 offset:37888
	ds_read_b128 v[198:201], v156 offset:38912
	ds_read_b128 v[202:205], v156 offset:39936
	global_load_lds_dwordx4 v[206:207], off
	v_lshl_add_u64 v[206:207], s[58:59], 0, v[130:131]
	s_mov_b32 m0, s67
	s_nop 0
	global_load_lds_dwordx4 v[206:207], off
	s_waitcnt lgkmcnt(8)
	s_barrier
	s_waitcnt lgkmcnt(0)
	s_setprio 1
	s_waitcnt lgkmcnt(0)
	v_mfma_f32_16x16x32_bf16 v[124:127], v[144:147], v[166:169], v[124:127]
	v_mfma_f32_16x16x32_bf16 v[120:123], v[158:161], v[166:169], v[120:123]
	v_mfma_f32_16x16x32_bf16 v[108:111], v[144:147], v[182:185], v[108:111]
	v_mfma_f32_16x16x32_bf16 v[104:107], v[158:161], v[182:185], v[104:107]
	v_mfma_f32_16x16x32_bf16 v[92:95], v[144:147], v[190:193], v[92:95]
	v_mfma_f32_16x16x32_bf16 v[88:91], v[158:161], v[190:193], v[88:91]
	v_mfma_f32_16x16x32_bf16 v[76:79], v[144:147], v[198:201], v[76:79]
	v_mfma_f32_16x16x32_bf16 v[72:75], v[158:161], v[198:201], v[72:75]
	v_mfma_f32_16x16x32_bf16 v[124:127], v[148:151], v[178:181], v[124:127]
	v_mfma_f32_16x16x32_bf16 v[120:123], v[162:165], v[178:181], v[120:123]
	v_mfma_f32_16x16x32_bf16 v[108:111], v[148:151], v[186:189], v[108:111]
	v_mfma_f32_16x16x32_bf16 v[104:107], v[162:165], v[186:189], v[104:107]
	v_mfma_f32_16x16x32_bf16 v[92:95], v[148:151], v[194:197], v[92:95]
	v_mfma_f32_16x16x32_bf16 v[88:91], v[162:165], v[194:197], v[88:91]
	v_mfma_f32_16x16x32_bf16 v[76:79], v[148:151], v[202:205], v[76:79]
	v_mfma_f32_16x16x32_bf16 v[72:75], v[162:165], v[202:205], v[72:75]
	s_setprio 0
	s_barrier
	s_add_i32 s58, 0, 0x1c000
	s_add_i32 s33, s33, s63
	v_add_u32_e32 v177, s58, v153
	v_lshl_add_u64 v[222:223], v[222:223], 0, s[16:17]
	s_mov_b32 m0, s33
	ds_read_b128 v[206:209], v177
	ds_read_b128 v[210:213], v177 offset:1024
	ds_read_b128 v[214:217], v177 offset:2048
	ds_read_b128 v[218:221], v177 offset:3072
	global_load_lds_dwordx4 v[222:223], off
	v_lshl_add_u64 v[222:223], v[224:225], 0, s[16:17]
	s_add_i32 m0, s33, 0x2000
	s_nop 0
	global_load_lds_dwordx4 v[222:223], off
	s_barrier
	s_waitcnt lgkmcnt(0)
	s_setprio 1
	s_waitcnt lgkmcnt(0)
	v_mfma_f32_16x16x32_bf16 v[116:119], v[206:209], v[166:169], v[116:119]
	v_mfma_f32_16x16x32_bf16 v[112:115], v[214:217], v[166:169], v[112:115]
	v_mfma_f32_16x16x32_bf16 v[100:103], v[206:209], v[182:185], v[100:103]
	v_mfma_f32_16x16x32_bf16 v[96:99], v[214:217], v[182:185], v[96:99]
	v_mfma_f32_16x16x32_bf16 v[84:87], v[206:209], v[190:193], v[84:87]
	v_mfma_f32_16x16x32_bf16 v[80:83], v[214:217], v[190:193], v[80:83]
	v_mfma_f32_16x16x32_bf16 v[68:71], v[206:209], v[198:201], v[68:71]
	v_mfma_f32_16x16x32_bf16 v[64:67], v[214:217], v[198:201], v[64:67]
	v_mfma_f32_16x16x32_bf16 v[116:119], v[210:213], v[178:181], v[116:119]
	v_mfma_f32_16x16x32_bf16 v[112:115], v[218:221], v[178:181], v[112:115]
	v_mfma_f32_16x16x32_bf16 v[100:103], v[210:213], v[186:189], v[100:103]
	v_mfma_f32_16x16x32_bf16 v[96:99], v[218:221], v[186:189], v[96:99]
	v_mfma_f32_16x16x32_bf16 v[84:87], v[210:213], v[194:197], v[84:87]
	v_mfma_f32_16x16x32_bf16 v[80:83], v[218:221], v[194:197], v[80:83]
	v_mfma_f32_16x16x32_bf16 v[68:71], v[210:213], v[202:205], v[68:71]
	v_mfma_f32_16x16x32_bf16 v[64:67], v[218:221], v[202:205], v[64:67]
	s_setprio 0
	s_mov_b32 m0, s68
	v_lshl_add_u64 v[222:223], s[56:57], 0, v[134:135]
	s_barrier
	ds_read_b128 v[166:169], v156 offset:49152
	ds_read_b128 v[178:181], v156 offset:50176
	ds_read_b128 v[182:185], v156 offset:51200
	ds_read_b128 v[186:189], v156 offset:52224
	ds_read_b128 v[190:193], v156 offset:53248
	ds_read_b128 v[194:197], v156 offset:54272
	ds_read_b128 v[198:201], v156 offset:55296
	ds_read_b128 v[202:205], v156 offset:56320
	global_load_lds_dwordx4 v[222:223], off
	v_lshl_add_u64 v[222:223], s[56:57], 0, v[130:131]
	s_mov_b32 m0, s69
	s_nop 0
	global_load_lds_dwordx4 v[222:223], off
	s_barrier
	s_waitcnt lgkmcnt(0)
	s_setprio 1
	s_waitcnt lgkmcnt(0)
	v_mfma_f32_16x16x32_bf16 v[60:63], v[144:147], v[166:169], v[60:63]
	v_mfma_f32_16x16x32_bf16 v[56:59], v[158:161], v[166:169], v[56:59]
	v_mfma_f32_16x16x32_bf16 v[44:47], v[144:147], v[182:185], v[44:47]
	v_mfma_f32_16x16x32_bf16 v[40:43], v[158:161], v[182:185], v[40:43]
	v_mfma_f32_16x16x32_bf16 v[28:31], v[144:147], v[190:193], v[28:31]
	v_mfma_f32_16x16x32_bf16 v[24:27], v[158:161], v[190:193], v[24:27]
	v_mfma_f32_16x16x32_bf16 v[12:15], v[144:147], v[198:201], v[12:15]
	v_mfma_f32_16x16x32_bf16 v[8:11], v[158:161], v[198:201], v[8:11]
	v_mfma_f32_16x16x32_bf16 v[60:63], v[148:151], v[178:181], v[60:63]
	v_mfma_f32_16x16x32_bf16 v[56:59], v[162:165], v[178:181], v[56:59]
	v_mfma_f32_16x16x32_bf16 v[44:47], v[148:151], v[186:189], v[44:47]
	v_mfma_f32_16x16x32_bf16 v[40:43], v[162:165], v[186:189], v[40:43]
	v_mfma_f32_16x16x32_bf16 v[28:31], v[148:151], v[194:197], v[28:31]
	v_mfma_f32_16x16x32_bf16 v[24:27], v[162:165], v[194:197], v[24:27]
	v_mfma_f32_16x16x32_bf16 v[12:15], v[148:151], v[202:205], v[12:15]
	v_mfma_f32_16x16x32_bf16 v[8:11], v[162:165], v[202:205], v[8:11]
	s_setprio 0
	s_barrier
	s_add_u32 s54, s54, 0x100080
	s_addc_u32 s55, s55, 0
	s_add_i32 s33, s58, s63
	v_lshl_add_u64 v[144:145], s[54:55], 0, v[132:133]
	s_mov_b32 m0, s33
	s_nop 0
	global_load_lds_dwordx4 v[144:145], off
	v_lshl_add_u64 v[144:145], s[54:55], 0, v[128:129]
	s_add_i32 m0, s33, 0x2000
	s_nop 0
	global_load_lds_dwordx4 v[144:145], off
	s_waitcnt vmcnt(6)
	s_barrier
	s_setprio 1
	v_mfma_f32_16x16x32_bf16 v[52:55], v[206:209], v[166:169], v[52:55]
	v_mfma_f32_16x16x32_bf16 v[48:51], v[214:217], v[166:169], v[48:51]
	v_mfma_f32_16x16x32_bf16 v[36:39], v[206:209], v[182:185], v[36:39]
	v_mfma_f32_16x16x32_bf16 v[32:35], v[214:217], v[182:185], v[32:35]
	v_mfma_f32_16x16x32_bf16 v[20:23], v[206:209], v[190:193], v[20:23]
	v_mfma_f32_16x16x32_bf16 v[16:19], v[214:217], v[190:193], v[16:19]
	v_mfma_f32_16x16x32_bf16 v[4:7], v[206:209], v[198:201], v[4:7]
	v_mfma_f32_16x16x32_bf16 v[0:3], v[214:217], v[198:201], v[0:3]
	v_mfma_f32_16x16x32_bf16 v[52:55], v[210:213], v[178:181], v[52:55]
	v_mfma_f32_16x16x32_bf16 v[48:51], v[218:221], v[178:181], v[48:51]
	v_mfma_f32_16x16x32_bf16 v[36:39], v[210:213], v[186:189], v[36:39]
	v_mfma_f32_16x16x32_bf16 v[32:35], v[218:221], v[186:189], v[32:35]
	v_mfma_f32_16x16x32_bf16 v[20:23], v[210:213], v[194:197], v[20:23]
	v_mfma_f32_16x16x32_bf16 v[16:19], v[218:221], v[194:197], v[16:19]
	v_mfma_f32_16x16x32_bf16 v[4:7], v[210:213], v[202:205], v[4:7]
	v_mfma_f32_16x16x32_bf16 v[0:3], v[218:221], v[202:205], v[0:3]
	s_setprio 0
	s_add_i32 s86, s86, 2
	s_add_u32 s84, s84, 0x100
	s_addc_u32 s85, s85, 0
	s_add_u32 s52, s52, 0x10000
	s_addc_u32 s53, s53, 0
	s_cmp_gt_u32 s86, 61
	s_barrier
	s_cbranch_scc0 .LBB0_1460
	s_lshl_b32 s82, s14, 8
	v_lshl_or_b32 v145, s81, 8, v154
	v_add_u32_e32 v144, s82, v152
	v_lshlrev_b32_e32 v145, 2, v145
	s_sub_u32 s83, s82, 0x1000
	s_lshr_b32 s83, s83, 11
	s_mul_i32 s83, s83, 6
	s_add_i32 s83, s83, 11
	s_cmp_gt_i32 s14, 15
	s_cselect_b32 s83, s83, 5
	s_lshl_b32 s83, s83, 12
	s_add_u32 s48, s72, s83
	s_addc_u32 s49, s73, 0
	v_lshl_add_u32 v146, v144, 12, v145
	global_load_dwordx4 v[148:151], v145, s[48:49]
	global_load_dwordx4 v[158:161], v145, s[48:49] offset:64
	global_load_dwordx4 v[162:165], v145, s[48:49] offset:512
	global_load_dwordx4 v[166:169], v145, s[48:49] offset:576
	s_mov_b64 s[84:85], s[24:25]
	s_mov_b64 s[86:87], s[24:25]
	v_mov_b32_e32 v226, 0
	v_mov_b32_e32 v227, 0
	v_mov_b32_e32 v228, 0
	v_mov_b32_e32 v229, 0
	v_mov_b32_e32 v230, 0
	v_mov_b32_e32 v231, 0
	v_mov_b32_e32 v232, 0
	v_mov_b32_e32 v233, 0
	global_load_dwordx4 v[178:181], v146, s[84:85]
	global_load_dwordx4 v[182:185], v146, s[84:85] offset:64
	global_load_dwordx4 v[186:189], v146, s[84:85] offset:512
	global_load_dwordx4 v[190:193], v146, s[84:85] offset:576
	s_add_u32 s84, s84, 0x10000
	s_addc_u32 s85, s85, 0
	global_load_dwordx4 v[194:197], v146, s[84:85]
	global_load_dwordx4 v[198:201], v146, s[84:85] offset:64
	global_load_dwordx4 v[202:205], v146, s[84:85] offset:512
	global_load_dwordx4 v[206:209], v146, s[84:85] offset:576
	s_add_u32 s84, s84, 0x10000
	s_addc_u32 s85, s85, 0
	global_load_dwordx4 v[210:213], v146, s[84:85]
	global_load_dwordx4 v[214:217], v146, s[84:85] offset:64
	global_load_dwordx4 v[218:221], v146, s[84:85] offset:512
	global_load_dwordx4 v[222:225], v146, s[84:85] offset:576
	s_waitcnt vmcnt(11)
	v_pk_fma_f32 v[124:125], v[124:125], v[148:149], v[178:179]
	v_pk_fma_f32 v[126:127], v[126:127], v[150:151], v[180:181]
	v_fmac_f32_e32 v226, v124, v124
	v_fmac_f32_e32 v226, v125, v125
	v_fmac_f32_e32 v226, v126, v126
	v_fmac_f32_e32 v226, v127, v127
	global_store_dwordx4 v146, v[124:127], s[86:87]
	s_add_u32 s84, s84, 0x10000
	s_addc_u32 s85, s85, 0
	global_load_dwordx4 v[178:181], v146, s[84:85]
	s_waitcnt vmcnt(12)
	v_pk_fma_f32 v[120:121], v[120:121], v[158:159], v[182:183]
	v_pk_fma_f32 v[122:123], v[122:123], v[160:161], v[184:185]
	v_fmac_f32_e32 v226, v120, v120
	v_fmac_f32_e32 v226, v121, v121
	v_fmac_f32_e32 v226, v122, v122
	v_fmac_f32_e32 v226, v123, v123
	global_store_dwordx4 v146, v[120:123], s[86:87] offset:64
	global_load_dwordx4 v[182:185], v146, s[84:85] offset:64
	s_waitcnt vmcnt(13)
	v_pk_fma_f32 v[116:117], v[116:117], v[162:163], v[186:187]
	v_pk_fma_f32 v[118:119], v[118:119], v[164:165], v[188:189]
	v_fmac_f32_e32 v226, v116, v116
	v_fmac_f32_e32 v226, v117, v117
	v_fmac_f32_e32 v226, v118, v118
	v_fmac_f32_e32 v226, v119, v119
	global_store_dwordx4 v146, v[116:119], s[86:87] offset:512
	global_load_dwordx4 v[186:189], v146, s[84:85] offset:512
	s_waitcnt vmcnt(14)
	v_pk_fma_f32 v[112:113], v[112:113], v[166:167], v[190:191]
	v_pk_fma_f32 v[114:115], v[114:115], v[168:169], v[192:193]
	v_fmac_f32_e32 v226, v112, v112
	v_fmac_f32_e32 v226, v113, v113
	v_fmac_f32_e32 v226, v114, v114
	v_fmac_f32_e32 v226, v115, v115
	global_store_dwordx4 v146, v[112:115], s[86:87] offset:576
	global_load_dwordx4 v[190:193], v146, s[84:85] offset:576
	s_add_u32 s86, s86, 0x10000
	s_addc_u32 s87, s87, 0
	s_waitcnt vmcnt(15)
	v_pk_fma_f32 v[108:109], v[108:109], v[148:149], v[194:195]
	v_pk_fma_f32 v[110:111], v[110:111], v[150:151], v[196:197]
	v_fmac_f32_e32 v227, v108, v108
	v_fmac_f32_e32 v227, v109, v109
	v_fmac_f32_e32 v227, v110, v110
	v_fmac_f32_e32 v227, v111, v111
	global_store_dwordx4 v146, v[108:111], s[86:87]
	s_add_u32 s84, s84, 0x50000
	s_addc_u32 s85, s85, 0
	global_load_dwordx4 v[194:197], v146, s[84:85]
	s_waitcnt vmcnt(16)
	v_pk_fma_f32 v[104:105], v[104:105], v[158:159], v[198:199]
	v_pk_fma_f32 v[106:107], v[106:107], v[160:161], v[200:201]
	v_fmac_f32_e32 v227, v104, v104
	v_fmac_f32_e32 v227, v105, v105
	v_fmac_f32_e32 v227, v106, v106
	v_fmac_f32_e32 v227, v107, v107
	global_store_dwordx4 v146, v[104:107], s[86:87] offset:64
	global_load_dwordx4 v[198:201], v146, s[84:85] offset:64
	s_waitcnt vmcnt(17)
	v_pk_fma_f32 v[100:101], v[100:101], v[162:163], v[202:203]
	v_pk_fma_f32 v[102:103], v[102:103], v[164:165], v[204:205]
	v_fmac_f32_e32 v227, v100, v100
	v_fmac_f32_e32 v227, v101, v101
	v_fmac_f32_e32 v227, v102, v102
	v_fmac_f32_e32 v227, v103, v103
	global_store_dwordx4 v146, v[100:103], s[86:87] offset:512
	global_load_dwordx4 v[202:205], v146, s[84:85] offset:512
	s_waitcnt vmcnt(18)
	v_pk_fma_f32 v[96:97], v[96:97], v[166:167], v[206:207]
	v_pk_fma_f32 v[98:99], v[98:99], v[168:169], v[208:209]
	v_fmac_f32_e32 v227, v96, v96
	v_fmac_f32_e32 v227, v97, v97
	v_fmac_f32_e32 v227, v98, v98
	v_fmac_f32_e32 v227, v99, v99
	global_store_dwordx4 v146, v[96:99], s[86:87] offset:576
	global_load_dwordx4 v[206:209], v146, s[84:85] offset:576
	s_add_u32 s86, s86, 0x10000
	s_addc_u32 s87, s87, 0
	s_waitcnt vmcnt(19)
	v_pk_fma_f32 v[92:93], v[92:93], v[148:149], v[210:211]
	v_pk_fma_f32 v[94:95], v[94:95], v[150:151], v[212:213]
	v_fmac_f32_e32 v228, v92, v92
	v_fmac_f32_e32 v228, v93, v93
	v_fmac_f32_e32 v228, v94, v94
	v_fmac_f32_e32 v228, v95, v95
	global_store_dwordx4 v146, v[92:95], s[86:87]
	s_add_u32 s84, s84, 0x10000
	s_addc_u32 s85, s85, 0
	global_load_dwordx4 v[210:213], v146, s[84:85]
	s_waitcnt vmcnt(20)
	v_pk_fma_f32 v[88:89], v[88:89], v[158:159], v[214:215]
	v_pk_fma_f32 v[90:91], v[90:91], v[160:161], v[216:217]
	v_fmac_f32_e32 v228, v88, v88
	v_fmac_f32_e32 v228, v89, v89
	v_fmac_f32_e32 v228, v90, v90
	v_fmac_f32_e32 v228, v91, v91
	global_store_dwordx4 v146, v[88:91], s[86:87] offset:64
	global_load_dwordx4 v[214:217], v146, s[84:85] offset:64
	s_waitcnt vmcnt(21)
	v_pk_fma_f32 v[84:85], v[84:85], v[162:163], v[218:219]
	v_pk_fma_f32 v[86:87], v[86:87], v[164:165], v[220:221]
	v_fmac_f32_e32 v228, v84, v84
	v_fmac_f32_e32 v228, v85, v85
	v_fmac_f32_e32 v228, v86, v86
	v_fmac_f32_e32 v228, v87, v87
	global_store_dwordx4 v146, v[84:87], s[86:87] offset:512
	global_load_dwordx4 v[218:221], v146, s[84:85] offset:512
	s_waitcnt vmcnt(22)
	v_pk_fma_f32 v[80:81], v[80:81], v[166:167], v[222:223]
	v_pk_fma_f32 v[82:83], v[82:83], v[168:169], v[224:225]
	v_fmac_f32_e32 v228, v80, v80
	v_fmac_f32_e32 v228, v81, v81
	v_fmac_f32_e32 v228, v82, v82
	v_fmac_f32_e32 v228, v83, v83
	global_store_dwordx4 v146, v[80:83], s[86:87] offset:576
	global_load_dwordx4 v[222:225], v146, s[84:85] offset:576
	s_add_u32 s86, s86, 0x10000
	s_addc_u32 s87, s87, 0
	s_waitcnt vmcnt(22)
	v_pk_fma_f32 v[76:77], v[76:77], v[148:149], v[178:179]
	v_pk_fma_f32 v[78:79], v[78:79], v[150:151], v[180:181]
	v_fmac_f32_e32 v229, v76, v76
	v_fmac_f32_e32 v229, v77, v77
	v_fmac_f32_e32 v229, v78, v78
	v_fmac_f32_e32 v229, v79, v79
	global_store_dwordx4 v146, v[76:79], s[86:87]
	s_add_u32 s84, s84, 0x10000
	s_addc_u32 s85, s85, 0
	global_load_dwordx4 v[178:181], v146, s[84:85]
	s_waitcnt vmcnt(22)
	v_pk_fma_f32 v[72:73], v[72:73], v[158:159], v[182:183]
	v_pk_fma_f32 v[74:75], v[74:75], v[160:161], v[184:185]
	v_fmac_f32_e32 v229, v72, v72
	v_fmac_f32_e32 v229, v73, v73
	v_fmac_f32_e32 v229, v74, v74
	v_fmac_f32_e32 v229, v75, v75
	global_store_dwordx4 v146, v[72:75], s[86:87] offset:64
	global_load_dwordx4 v[182:185], v146, s[84:85] offset:64
	s_waitcnt vmcnt(22)
	v_pk_fma_f32 v[68:69], v[68:69], v[162:163], v[186:187]
	v_pk_fma_f32 v[70:71], v[70:71], v[164:165], v[188:189]
	v_fmac_f32_e32 v229, v68, v68
	v_fmac_f32_e32 v229, v69, v69
	v_fmac_f32_e32 v229, v70, v70
	v_fmac_f32_e32 v229, v71, v71
	global_store_dwordx4 v146, v[68:71], s[86:87] offset:512
	global_load_dwordx4 v[186:189], v146, s[84:85] offset:512
	s_waitcnt vmcnt(22)
	v_pk_fma_f32 v[64:65], v[64:65], v[166:167], v[190:191]
	v_pk_fma_f32 v[66:67], v[66:67], v[168:169], v[192:193]
	v_fmac_f32_e32 v229, v64, v64
	v_fmac_f32_e32 v229, v65, v65
	v_fmac_f32_e32 v229, v66, v66
	v_fmac_f32_e32 v229, v67, v67
	global_store_dwordx4 v146, v[64:67], s[86:87] offset:576
	global_load_dwordx4 v[190:193], v146, s[84:85] offset:576
	s_add_u32 s86, s86, 0x50000
	s_addc_u32 s87, s87, 0
	s_waitcnt vmcnt(22)
	v_pk_fma_f32 v[60:61], v[60:61], v[148:149], v[194:195]
	v_pk_fma_f32 v[62:63], v[62:63], v[150:151], v[196:197]
	v_fmac_f32_e32 v230, v60, v60
	v_fmac_f32_e32 v230, v61, v61
	v_fmac_f32_e32 v230, v62, v62
	v_fmac_f32_e32 v230, v63, v63
	global_store_dwordx4 v146, v[60:63], s[86:87]
	s_add_u32 s84, s84, 0x10000
	s_addc_u32 s85, s85, 0
	global_load_dwordx4 v[194:197], v146, s[84:85]
	s_waitcnt vmcnt(22)
	v_pk_fma_f32 v[56:57], v[56:57], v[158:159], v[198:199]
	v_pk_fma_f32 v[58:59], v[58:59], v[160:161], v[200:201]
	v_fmac_f32_e32 v230, v56, v56
	v_fmac_f32_e32 v230, v57, v57
	v_fmac_f32_e32 v230, v58, v58
	v_fmac_f32_e32 v230, v59, v59
	global_store_dwordx4 v146, v[56:59], s[86:87] offset:64
	global_load_dwordx4 v[198:201], v146, s[84:85] offset:64
	s_waitcnt vmcnt(22)
	v_pk_fma_f32 v[52:53], v[52:53], v[162:163], v[202:203]
	v_pk_fma_f32 v[54:55], v[54:55], v[164:165], v[204:205]
	v_fmac_f32_e32 v230, v52, v52
	v_fmac_f32_e32 v230, v53, v53
	v_fmac_f32_e32 v230, v54, v54
	v_fmac_f32_e32 v230, v55, v55
	global_store_dwordx4 v146, v[52:55], s[86:87] offset:512
	global_load_dwordx4 v[202:205], v146, s[84:85] offset:512
	s_waitcnt vmcnt(22)
	v_pk_fma_f32 v[48:49], v[48:49], v[166:167], v[206:207]
	v_pk_fma_f32 v[50:51], v[50:51], v[168:169], v[208:209]
	v_fmac_f32_e32 v230, v48, v48
	v_fmac_f32_e32 v230, v49, v49
	v_fmac_f32_e32 v230, v50, v50
	v_fmac_f32_e32 v230, v51, v51
	global_store_dwordx4 v146, v[48:51], s[86:87] offset:576
	global_load_dwordx4 v[206:209], v146, s[84:85] offset:576
	s_add_u32 s86, s86, 0x10000
	s_addc_u32 s87, s87, 0
	s_waitcnt vmcnt(22)
	v_pk_fma_f32 v[44:45], v[44:45], v[148:149], v[210:211]
	v_pk_fma_f32 v[46:47], v[46:47], v[150:151], v[212:213]
	v_fmac_f32_e32 v231, v44, v44
	v_fmac_f32_e32 v231, v45, v45
	v_fmac_f32_e32 v231, v46, v46
	v_fmac_f32_e32 v231, v47, v47
	global_store_dwordx4 v146, v[44:47], s[86:87]
	s_waitcnt vmcnt(21)
	v_pk_fma_f32 v[40:41], v[40:41], v[158:159], v[214:215]
	v_pk_fma_f32 v[42:43], v[42:43], v[160:161], v[216:217]
	v_fmac_f32_e32 v231, v40, v40
	v_fmac_f32_e32 v231, v41, v41
	v_fmac_f32_e32 v231, v42, v42
	v_fmac_f32_e32 v231, v43, v43
	global_store_dwordx4 v146, v[40:43], s[86:87] offset:64
	s_waitcnt vmcnt(20)
	v_pk_fma_f32 v[36:37], v[36:37], v[162:163], v[218:219]
	v_pk_fma_f32 v[38:39], v[38:39], v[164:165], v[220:221]
	v_fmac_f32_e32 v231, v36, v36
	v_fmac_f32_e32 v231, v37, v37
	v_fmac_f32_e32 v231, v38, v38
	v_fmac_f32_e32 v231, v39, v39
	global_store_dwordx4 v146, v[36:39], s[86:87] offset:512
	s_waitcnt vmcnt(19)
	v_pk_fma_f32 v[32:33], v[32:33], v[166:167], v[222:223]
	v_pk_fma_f32 v[34:35], v[34:35], v[168:169], v[224:225]
	v_fmac_f32_e32 v231, v32, v32
	v_fmac_f32_e32 v231, v33, v33
	v_fmac_f32_e32 v231, v34, v34
	v_fmac_f32_e32 v231, v35, v35
	global_store_dwordx4 v146, v[32:35], s[86:87] offset:576
	s_add_u32 s86, s86, 0x10000
	s_addc_u32 s87, s87, 0
	s_waitcnt vmcnt(18)
	v_pk_fma_f32 v[28:29], v[28:29], v[148:149], v[178:179]
	v_pk_fma_f32 v[30:31], v[30:31], v[150:151], v[180:181]
	v_fmac_f32_e32 v232, v28, v28
	v_fmac_f32_e32 v232, v29, v29
	v_fmac_f32_e32 v232, v30, v30
	v_fmac_f32_e32 v232, v31, v31
	global_store_dwordx4 v146, v[28:31], s[86:87]
	s_waitcnt vmcnt(17)
	v_pk_fma_f32 v[24:25], v[24:25], v[158:159], v[182:183]
	v_pk_fma_f32 v[26:27], v[26:27], v[160:161], v[184:185]
	v_fmac_f32_e32 v232, v24, v24
	v_fmac_f32_e32 v232, v25, v25
	v_fmac_f32_e32 v232, v26, v26
	v_fmac_f32_e32 v232, v27, v27
	global_store_dwordx4 v146, v[24:27], s[86:87] offset:64
	s_waitcnt vmcnt(16)
	v_pk_fma_f32 v[20:21], v[20:21], v[162:163], v[186:187]
	v_pk_fma_f32 v[22:23], v[22:23], v[164:165], v[188:189]
	v_fmac_f32_e32 v232, v20, v20
	v_fmac_f32_e32 v232, v21, v21
	v_fmac_f32_e32 v232, v22, v22
	v_fmac_f32_e32 v232, v23, v23
	global_store_dwordx4 v146, v[20:23], s[86:87] offset:512
	s_waitcnt vmcnt(15)
	v_pk_fma_f32 v[16:17], v[16:17], v[166:167], v[190:191]
	v_pk_fma_f32 v[18:19], v[18:19], v[168:169], v[192:193]
	v_fmac_f32_e32 v232, v16, v16
	v_fmac_f32_e32 v232, v17, v17
	v_fmac_f32_e32 v232, v18, v18
	v_fmac_f32_e32 v232, v19, v19
	global_store_dwordx4 v146, v[16:19], s[86:87] offset:576
	s_add_u32 s86, s86, 0x10000
	s_addc_u32 s87, s87, 0
	s_waitcnt vmcnt(14)
	v_pk_fma_f32 v[12:13], v[12:13], v[148:149], v[194:195]
	v_pk_fma_f32 v[14:15], v[14:15], v[150:151], v[196:197]
	v_fmac_f32_e32 v233, v12, v12
	v_fmac_f32_e32 v233, v13, v13
	v_fmac_f32_e32 v233, v14, v14
	v_fmac_f32_e32 v233, v15, v15
	global_store_dwordx4 v146, v[12:15], s[86:87]
	s_waitcnt vmcnt(13)
	v_pk_fma_f32 v[8:9], v[8:9], v[158:159], v[198:199]
	v_pk_fma_f32 v[10:11], v[10:11], v[160:161], v[200:201]
	v_fmac_f32_e32 v233, v8, v8
	v_fmac_f32_e32 v233, v9, v9
	v_fmac_f32_e32 v233, v10, v10
	v_fmac_f32_e32 v233, v11, v11
	global_store_dwordx4 v146, v[8:11], s[86:87] offset:64
	s_waitcnt vmcnt(12)
	v_pk_fma_f32 v[4:5], v[4:5], v[162:163], v[202:203]
	v_pk_fma_f32 v[6:7], v[6:7], v[164:165], v[204:205]
	v_fmac_f32_e32 v233, v4, v4
	v_fmac_f32_e32 v233, v5, v5
	v_fmac_f32_e32 v233, v6, v6
	v_fmac_f32_e32 v233, v7, v7
	global_store_dwordx4 v146, v[4:7], s[86:87] offset:512
	s_waitcnt vmcnt(11)
	v_pk_fma_f32 v[0:1], v[0:1], v[166:167], v[206:207]
	v_pk_fma_f32 v[2:3], v[2:3], v[168:169], v[208:209]
	v_fmac_f32_e32 v233, v0, v0
	v_fmac_f32_e32 v233, v1, v1
	v_fmac_f32_e32 v233, v2, v2
	v_fmac_f32_e32 v233, v3, v3
	global_store_dwordx4 v146, v[0:3], s[86:87] offset:576
	s_mov_b32 s81, s34
	s_mov_b64 s[52:53], s[50:51]
	s_mov_b64 s[54:55], s[40:41]
	s_mov_b32 s14, s36
	s_and_b64 vcc, exec, s[12:13]
	s_cbranch_vccz .LBB0_1457
	s_waitcnt vmcnt(0)
	s_cmpk_gt_u32 s60, 0xff
	s_cbranch_scc1 .LBB0_1464
	s_barrier

.LBB0_1467:
	s_lshr_b32 s12, s3, 29
	s_add_i32 s12, s2, s12
	s_ashr_i32 s13, s12, 3
	s_and_b32 s12, s12, -8
	s_sub_i32 s12, s2, s12
	s_lshr_b32 s14, s12, 31
	s_or_b32 s14, s14, 24
	s_mul_i32 s12, s14, s12
	s_add_i32 s12, s12, s13
	s_ashr_i32 s13, s12, 31
	s_lshr_b32 s13, s13, 27
	s_add_i32 s13, s12, s13
	s_ashr_i32 s28, s13, 5
	s_lshl_b32 s14, s28, 3
	s_sub_i32 s13, 48, s14
	s_min_u32 s15, s13, 8
	s_lshl_b32 s13, s28, 5
	s_sub_i32 s16, s12, s13
	s_sext_i32_i8 s12, s16
	v_cvt_f32_ubyte0_e32 v1, s15
	v_cvt_f32_i32_e32 v0, s12
	v_rcp_iflag_f32_e32 v2, v1
	s_ashr_i32 s12, s12, 30
	s_or_b32 s17, s12, 1
	v_mul_f32_e32 v2, v0, v2
	v_trunc_f32_e32 v2, v2
	v_fma_f32 v0, -v2, v1, v0
	v_cvt_i32_f32_e32 v2, v2
	v_cmp_ge_f32_e64 s[12:13], |v0|, v1
	s_and_b64 s[12:13], s[12:13], exec
	s_cselect_b32 s12, s17, 0
	v_readfirstlane_b32 s30, v2
	s_add_i32 s30, s30, s12
	s_mul_i32 s12, s30, s15
	s_sub_i32 s12, s16, s12
	s_sext_i32_i8 s29, s12
	s_add_i32 s12, s14, s29
	v_and_b32_e32 v178, 63, v170
	v_lshrrev_b32_e32 v179, 6, v170
	v_and_b32_e32 v180, 15, v178
	v_and_b32_e32 v181, 3, v179
	v_lshrrev_b32_e32 v179, 2, v179
	v_lshl_add_u32 v180, v179, 6, v180
	v_lshlrev_b32_e32 v180, 2, v180
	v_lshl_add_u32 v180, v181, 10, v180
	v_add_u32_e32 v180, 0x20000, v180
	ds_bpermute_b32 v182, v172, v226
	ds_bpermute_b32 v183, v172, v227
	ds_bpermute_b32 v184, v172, v228
	ds_bpermute_b32 v185, v172, v229
	ds_bpermute_b32 v186, v172, v230
	ds_bpermute_b32 v187, v172, v231
	ds_bpermute_b32 v188, v172, v232
	ds_bpermute_b32 v189, v172, v233
	s_waitcnt lgkmcnt(7)
	v_add_f32_e32 v226, v226, v182
	s_waitcnt lgkmcnt(6)
	v_add_f32_e32 v227, v227, v183
	s_waitcnt lgkmcnt(5)
	v_add_f32_e32 v228, v228, v184
	s_waitcnt lgkmcnt(4)
	v_add_f32_e32 v229, v229, v185
	s_waitcnt lgkmcnt(3)
	v_add_f32_e32 v230, v230, v186
	s_waitcnt lgkmcnt(2)
	v_add_f32_e32 v231, v231, v187
	s_waitcnt lgkmcnt(1)
	v_add_f32_e32 v232, v232, v188
	s_waitcnt lgkmcnt(0)
	v_add_f32_e32 v233, v233, v189
	ds_bpermute_b32 v182, v171, v226
	ds_bpermute_b32 v183, v171, v227
	ds_bpermute_b32 v184, v171, v228
	ds_bpermute_b32 v185, v171, v229
	ds_bpermute_b32 v186, v171, v230
	ds_bpermute_b32 v187, v171, v231
	ds_bpermute_b32 v188, v171, v232
	ds_bpermute_b32 v189, v171, v233
	s_waitcnt lgkmcnt(7)
	v_add_f32_e32 v226, v226, v182
	s_waitcnt lgkmcnt(6)
	v_add_f32_e32 v227, v227, v183
	s_waitcnt lgkmcnt(5)
	v_add_f32_e32 v228, v228, v184
	s_waitcnt lgkmcnt(4)
	v_add_f32_e32 v229, v229, v185
	s_waitcnt lgkmcnt(3)
	v_add_f32_e32 v230, v230, v186
	s_waitcnt lgkmcnt(2)
	v_add_f32_e32 v231, v231, v187
	s_waitcnt lgkmcnt(1)
	v_add_f32_e32 v232, v232, v188
	s_waitcnt lgkmcnt(0)
	v_add_f32_e32 v233, v233, v189
	ds_write_b32 v180, v226
	ds_write_b32 v180, v227 offset:64
	ds_write_b32 v180, v228 offset:128
	ds_write_b32 v180, v229 offset:192
	ds_write_b32 v180, v230 offset:512
	ds_write_b32 v180, v231 offset:576
	ds_write_b32 v180, v232 offset:640
	ds_write_b32 v180, v233 offset:704
	s_waitcnt lgkmcnt(0)
	s_barrier
	v_readfirstlane_b32 s60, v170
	s_and_b32 s62, s30, 3
	s_lshl_b32 s61, s12, 2
	s_add_i32 s61, s61, s62
	s_lshl_b32 s61, s61, 10
	s_add_u32 s62, s22, s61
	s_addc_u32 s63, s23, 0
	s_add_u32 s62, s62, 0x40000
	s_addc_u32 s63, s63, 0
	s_cmp_lt_u32 s60, 256
	s_cbranch_scc0 .Lf2p10_nop
	v_lshlrev_b32_e32 v190, 2, v170
	v_add_u32_e32 v191, 0x20000, v190
	ds_read_b32 v192, v191
	ds_read_b32 v193, v191 offset:1024
	ds_read_b32 v194, v191 offset:2048
	ds_read_b32 v195, v191 offset:3072
	s_waitcnt lgkmcnt(0)
	v_add_f32_e32 v192, v192, v193
	v_add_f32_e32 v194, v194, v195
	v_add_f32_e32 v192, v192, v194
	global_store_dword v190, v192, s[62:63] sc1
.Lf2p10_nop:
	s_waitcnt vmcnt(0)
	s_barrier
	s_and_saveexec_b64 s[14:15], s[38:39]
	s_cbranch_execz .LBB0_1479
	s_ashr_i32 s13, s12, 31
	s_lshl_b64 s[16:17], s[12:13], 2
	s_mov_b64 s[18:19], exec
	s_add_u32 s13, s22, s16
	s_addc_u32 s17, s23, s17
	buffer_wbl2 sc1
	s_waitcnt vmcnt(0) lgkmcnt(0)
	s_waitcnt vmcnt(0)
	v_mbcnt_lo_u32_b32 v0, s18, 0
	s_add_u32 s16, s13, 0x779b900
	v_mbcnt_hi_u32_b32 v0, s19, v0
	s_addc_u32 s17, s17, 0
	v_cmp_eq_u32_e32 vcc, 0, v0
	s_and_saveexec_b64 s[26:27], vcc
	s_cbranch_execz .LBB0_1470
	s_bcnt1_i32_b64 s13, s[18:19]
	v_mov_b32_e32 v0, 0
	v_mov_b32_e32 v1, s13
	global_atomic_add v0, v1, s[16:17]

.LBB0_1479:
	s_or_b64 exec, exec, s[14:15]
	s_sext_i32_i8 s13, s30
	s_lshl_b32 s12, s12, 8
	s_lshl_b32 s16, s13, 6
	s_add_i32 s50, s12, s16
	s_add_u32 s40, s22, 0x56bc000
	s_addc_u32 s41, s23, 0
	s_add_i32 s50, s50, 64
	s_add_u32 s26, s22, 0x76bc000
	s_addc_u32 s27, s23, 0
	s_lshl_b32 s18, s29, 8
	s_lshl_b32 s17, s28, 11
	s_add_i32 s16, s16, s18
	v_lshrrev_b32_e32 v1, 6, v170
	s_add_i32 s16, s16, s17
	v_mov_b32_e32 v0, v170
	v_or_b32_e32 v50, s16, v1
	s_waitcnt lgkmcnt(0)
	s_barrier
	s_load_dwordx2 s[52:53], s[0:1], 0xe8
	s_sub_i32 s66, s50, 64
	v_readfirstlane_b32 s60, v170
	v_and_b32_e32 v194, 63, v170
	v_lshrrev_b32_e32 v195, 6, v170
	v_and_b32_e32 v196, 15, v194
	v_lshrrev_b32_e32 v194, 4, v194
	v_and_b32_e32 v197, 3, v195
	v_lshrrev_b32_e32 v195, 2, v195
	v_lshl_add_u32 v196, v195, 6, v196
	v_lshl_add_u32 v197, v197, 5, 0
	v_lshl_add_u32 v197, v194, 2, v197
	s_lshr_b32 s64, s66, 8
	s_lshr_b32 s65, s66, 6
	s_and_b32 s65, s65, 3
	s_lshl_b32 s67, s65, 8
	v_add_u32_e32 v197, s67, v197
	s_waitcnt lgkmcnt(0)
	s_lshl_b32 s61, s64, 12
	s_add_u32 s62, s52, s61
	s_addc_u32 s63, s53, 0
	s_add_u32 s62, s62, 0x40000
	s_addc_u32 s63, s63, 0
	s_cmp_lt_u32 s60, 256
	s_cbranch_scc0 .Lf2p10_nor
	v_lshlrev_b32_e32 v190, 2, v170
	global_load_dword v192, v190, s[62:63] sc1
	global_load_dword v193, v190, s[62:63] offset:1024 sc1
	global_load_dword v198, v190, s[62:63] offset:2048 sc1
	global_load_dword v199, v190, s[62:63] offset:3072 sc1
	v_mov_b32_e32 v191, 0x358637bd
	s_waitcnt vmcnt(0)
	v_add_f32_e32 v192, v192, v193
	v_add_f32_e32 v198, v198, v199
	v_add_f32_e32 v192, v192, v198
	v_fmamk_f32 v192, v192, 0x3a800000, v191
	v_rsq_f32_e32 v192, v192
	v_add_u32_e32 v191, 0x21000, v190
	s_nop 0
	ds_write_b32 v191, v192
	s_cmp_lg_u32 s65, 0
	s_cbranch_scc1 .Lf2p10_nor
	s_lshl_b32 s61, s64, 10
	s_add_u32 s62, s52, 0x76bc000
	s_addc_u32 s63, s53, 0
	s_add_u32 s62, s62, s61
	s_addc_u32 s63, s63, 0
	global_store_dword v190, v192, s[62:63]
.Lf2p10_nor:
	s_waitcnt lgkmcnt(0)
	s_barrier
	s_mov_b64 s[28:29], 0
